# v038 plus norm-loop second-row loads issued before waiting on the first row
# baseline (speedup 1.0000x reference)
; DEVQ float wave_sum(float v) {
; #pragma unroll
;     for (int o = 1; o < 64; o <<= 1) v += __shfl_xor(v, o);
;     return v;
; }
; #pragma unroll
;     for (int j = 0; j < 4; ++j) { r.v[j] = src ? ((const f32x4*)src)[lane + 64 * j] : (f32x4){0.f, 0.f, 0.f, 0.f}; r.ss += (r.v[j].x * r.v[j].x + r.v[j].y * r.v[j].y) + (r.v[j].z * r.v[j].z + r.v[j].w * r.v[j].w); }
;     return r; }
.LBB0_183:
	v_lshl_add_u64 v[0:1], s[18:19], 0, v[42:43]
	v_add_co_u32_e32 v2, vcc, 0x3200000, v0
	s_addk_i32 s4, 0x780
	s_nop 0
	v_addc_co_u32_e32 v3, vcc, 0, v1, vcc
	global_load_dwordx4 v[28:31], v[2:3], off
	global_load_dwordx4 v[24:27], v[2:3], off offset:1024
	global_load_dwordx4 v[20:23], v[2:3], off offset:2048
	global_load_dwordx4 v[16:19], v[2:3], off offset:3072
	v_add_co_u32_e32 v0, vcc, s30, v0
	v_lshl_add_u64 v[42:43], v[42:43], 0, s[14:15]
	s_nop 0
	v_addc_co_u32_e32 v1, vcc, 0, v1, vcc
	s_cmp_gt_i32 s4, 0x987f
	global_load_dwordx4 v[12:15], v[0:1], off
	global_load_dwordx4 v[8:11], v[0:1], off offset:1024
	global_load_dwordx4 v[4:7], v[0:1], off offset:2048
	global_load_dwordx4 v[0:3], v[0:1], off offset:3072
	s_waitcnt vmcnt(4) lgkmcnt(0)
	v_mul_f32_e32 v80, v29, v29
	v_mul_f32_e32 v81, v31, v31
	v_fmac_f32_e32 v80, v28, v28
	v_fmac_f32_e32 v81, v30, v30
	v_add_f32_e32 v80, v80, v81
	v_mul_f32_e32 v81, v25, v25
	v_mul_f32_e32 v82, v27, v27
	v_fmac_f32_e32 v81, v24, v24
	v_fmac_f32_e32 v82, v26, v26
	v_add_f32_e32 v81, v81, v82
	v_add_f32_e32 v80, v80, v81
	v_mul_f32_e32 v81, v21, v21
	v_mul_f32_e32 v82, v23, v23
	v_fmac_f32_e32 v81, v20, v20
	v_fmac_f32_e32 v82, v22, v22
	v_add_f32_e32 v81, v81, v82
	v_add_f32_e32 v80, v80, v81
	v_mul_f32_e32 v81, v17, v17
	v_mul_f32_e32 v82, v19, v19
	v_fmac_f32_e32 v81, v16, v16
	v_fmac_f32_e32 v82, v18, v18
	v_add_f32_e32 v81, v81, v82
	v_add_f32_e32 v51, v80, v81
	s_waitcnt vmcnt(0)
	v_mul_f32_e32 v50, v13, v13
	v_mul_f32_e32 v52, v15, v15
	v_fmac_f32_e32 v50, v12, v12
	v_fmac_f32_e32 v52, v14, v14
	v_add_f32_e32 v50, v50, v52
	v_mul_f32_e32 v52, v9, v9
	v_mul_f32_e32 v53, v11, v11
	v_fmac_f32_e32 v52, v8, v8
	v_fmac_f32_e32 v53, v10, v10
	v_add_f32_e32 v52, v52, v53
	v_add_f32_e32 v50, v50, v52
	v_mul_f32_e32 v52, v5, v5
	v_mul_f32_e32 v53, v7, v7
	v_fmac_f32_e32 v52, v4, v4
	v_fmac_f32_e32 v53, v6, v6
	v_add_f32_e32 v52, v52, v53
	v_add_f32_e32 v50, v50, v52
	v_mul_f32_e32 v52, v1, v1
	v_mul_f32_e32 v53, v3, v3
	v_fmac_f32_e32 v52, v0, v0
	v_fmac_f32_e32 v53, v2, v2
	v_add_f32_e32 v52, v52, v53
	v_add_f32_e32 v50, v50, v52
	ds_bpermute_b32 v52, v44, v51
	ds_bpermute_b32 v97, v44, v50
	s_waitcnt lgkmcnt(0)
	v_add_f32_e32 v51, v51, v52
	v_add_f32_e32 v96, v50, v97
	ds_bpermute_b32 v52, v45, v51
	ds_bpermute_b32 v97, v45, v96
	s_waitcnt lgkmcnt(0)
	v_add_f32_e32 v51, v51, v52
	v_add_f32_e32 v96, v96, v97
	ds_bpermute_b32 v52, v46, v51
	ds_bpermute_b32 v97, v46, v96
	s_waitcnt lgkmcnt(0)
	v_add_f32_e32 v51, v51, v52
	v_add_f32_e32 v96, v96, v97
	ds_bpermute_b32 v52, v47, v51
	ds_bpermute_b32 v97, v47, v96
	s_waitcnt lgkmcnt(0)
	v_add_f32_e32 v51, v51, v52
	v_add_f32_e32 v96, v96, v97
	ds_bpermute_b32 v52, v48, v51
	ds_bpermute_b32 v97, v48, v96
	s_waitcnt lgkmcnt(0)
	v_add_f32_e32 v51, v51, v52
	v_add_f32_e32 v96, v96, v97
	ds_bpermute_b32 v52, v49, v51
	ds_bpermute_b32 v97, v49, v96
	s_waitcnt lgkmcnt(0)
	v_add_f32_e32 v51, v51, v52
	v_add_f32_e32 v96, v96, v97
	v_fmamk_f32 v51, v51, 0x3a800000, v178
	v_cmp_gt_f32_e32 vcc, s28, v51
	v_mul_f32_e32 v52, 0x4f800000, v51
	s_nop 0
	v_cndmask_b32_e32 v51, v51, v52, vcc
	v_sqrt_f32_e32 v52, v51
	s_nop 0
	v_add_u32_e32 v53, -1, v52
	v_fma_f32 v54, -v53, v52, v51
	v_cmp_ge_f32_e64 s[0:1], 0, v54
	v_add_u32_e32 v54, 1, v52
	s_nop 0
	v_cndmask_b32_e64 v53, v52, v53, s[0:1]
	v_fma_f32 v52, -v54, v52, v51
	v_cmp_lt_f32_e64 s[0:1], 0, v52
	s_nop 1
	v_cndmask_b32_e64 v52, v53, v54, s[0:1]
	v_mul_f32_e32 v53, 0x37800000, v52
	v_cndmask_b32_e32 v52, v52, v53, vcc
	v_cmp_class_f32_e32 vcc, v51, v179
	s_nop 1
	v_cndmask_b32_e32 v51, v52, v51, vcc
	v_div_scale_f32 v52, s[0:1], v51, v51, 1.0
	v_rcp_f32_e32 v53, v52
	s_nop 0
	v_fma_f32 v54, -v52, v53, 1.0
	v_fmac_f32_e32 v53, v54, v53
	v_div_scale_f32 v54, vcc, 1.0, v51, 1.0
	v_mul_f32_e32 v55, v54, v53
	v_fma_f32 v56, -v52, v55, v54
	v_fmac_f32_e32 v55, v56, v53
	v_fma_f32 v52, -v52, v55, v54
	v_div_fmas_f32 v52, v52, v53, v55
	v_div_fixup_f32 v51, v52, v51, 1.0
	v_mul_f32_e32 v28, v28, v51
	v_mul_f32_e32 v29, v29, v51
	v_mul_f32_e32 v24, v24, v51
	v_mul_f32_e32 v25, v25, v51
	v_mul_f32_e32 v20, v20, v51
	v_mul_f32_e32 v21, v21, v51
	v_mul_f32_e32 v16, v16, v51
	v_mul_f32_e32 v17, v17, v51
	v_mul_f32_e32 v28, v64, v28
	v_mul_f32_e32 v29, v65, v29
	v_bfe_u32 v52, v28, 16, 1
	v_add3_u32 v28, v28, v52, s60
	v_bfe_u32 v52, v29, 16, 1
	v_lshrrev_b32_e32 v28, 16, v28
	v_add3_u32 v29, v29, v52, s60
	v_and_or_b32 v52, v29, s61, v28
	v_mul_f32_e32 v28, v30, v51
	v_mul_f32_e32 v28, v66, v28
	v_mul_f32_e32 v29, v31, v51
	v_mul_f32_e32 v29, v67, v29
	v_bfe_u32 v30, v28, 16, 1
	v_add3_u32 v28, v28, v30, s60
	v_bfe_u32 v30, v29, 16, 1
	v_lshrrev_b32_e32 v28, 16, v28
	v_add3_u32 v29, v29, v30, s60
	v_and_or_b32 v53, v29, s61, v28
	v_lshl_add_u64 v[28:29], s[18:19], 0, v[40:41]
	v_add_co_u32_e32 v28, vcc, s31, v28
	s_nop 1
	v_addc_co_u32_e32 v29, vcc, 0, v29, vcc
	flat_store_dwordx2 v[28:29], v[52:53]
	v_mul_f32_e32 v24, v68, v24
	v_mul_f32_e32 v25, v69, v25
	v_bfe_u32 v30, v24, 16, 1
	v_add3_u32 v24, v24, v30, s60
	v_bfe_u32 v30, v25, 16, 1
	v_lshrrev_b32_e32 v24, 16, v24
	v_add3_u32 v25, v25, v30, s60
; DEVQ unsigned pk2(float lo, float hi) { return f2bf(lo) | (f2bf(hi) << 16); }
; DEVQ void row_finish(const RowV& r, const float* g, bf16* urow, float* hcopy, const float* hbias, int lane) {
;     const float rstd = 1.0f / sqrtf(wave_sum(r.ss) * (1.0f / D) + RMS_EPS);
; #pragma unroll
;     for (int j = 0; j < 4; ++j) { const f32x4 gv = ((const f32x4*)g)[lane + 64 * j];
;         if (hcopy) ((f32x4*)hcopy)[lane + 64 * j] = r.v[j] + ((const f32x4*)hbias)[lane + 64 * j];
;         ((unsigned long long*)urow)[lane + 64 * j] = (unsigned long long)pk2(r.v[j].x * rstd * gv.x, r.v[j].y * rstd * gv.y) | ((unsigned long long)pk2(r.v[j].z * rstd * gv.z, r.v[j].w * rstd * gv.w) << 32); }
; }
	v_and_or_b32 v24, v25, s61, v24
	v_mul_f32_e32 v25, v26, v51
	v_mul_f32_e32 v25, v70, v25
	v_mul_f32_e32 v26, v27, v51
	v_mul_f32_e32 v26, v71, v26
	v_bfe_u32 v27, v25, 16, 1
	v_add3_u32 v25, v25, v27, s60
	v_bfe_u32 v27, v26, 16, 1
	v_lshrrev_b32_e32 v25, 16, v25
	v_add3_u32 v26, v26, v27, s60
	v_and_or_b32 v25, v26, s61, v25
	flat_store_dwordx2 v[28:29], v[24:25] offset:512
	v_mul_f32_e32 v20, v72, v20
	v_mul_f32_e32 v21, v73, v21
	v_bfe_u32 v24, v20, 16, 1
	v_add3_u32 v20, v20, v24, s60
	v_bfe_u32 v24, v21, 16, 1
	v_lshrrev_b32_e32 v20, 16, v20
	v_add3_u32 v21, v21, v24, s60
	v_and_or_b32 v20, v21, s61, v20
	v_mul_f32_e32 v21, v22, v51
	v_mul_f32_e32 v21, v74, v21
	v_mul_f32_e32 v22, v23, v51
	v_mul_f32_e32 v22, v75, v22
	v_bfe_u32 v23, v21, 16, 1
	v_add3_u32 v21, v21, v23, s60
	v_bfe_u32 v23, v22, 16, 1
	v_lshrrev_b32_e32 v21, 16, v21
	v_add3_u32 v22, v22, v23, s60
	v_and_or_b32 v21, v22, s61, v21
	flat_store_dwordx2 v[28:29], v[20:21] offset:1024
	v_mul_f32_e32 v16, v16, v76
	v_mul_f32_e32 v17, v17, v77
	v_bfe_u32 v20, v16, 16, 1
	v_add3_u32 v16, v16, v20, s60
	v_bfe_u32 v20, v17, 16, 1
	v_lshrrev_b32_e32 v16, 16, v16
	v_add3_u32 v17, v17, v20, s60
	v_and_or_b32 v16, v17, s61, v16
	v_mul_f32_e32 v17, v18, v51
	v_mul_f32_e32 v17, v17, v78
	v_mul_f32_e32 v18, v19, v51
	v_mul_f32_e32 v18, v18, v79
	v_bfe_u32 v19, v17, 16, 1
	v_add3_u32 v17, v17, v19, s60
	v_bfe_u32 v19, v18, 16, 1
	v_lshrrev_b32_e32 v17, 16, v17
	v_add3_u32 v18, v18, v19, s60
	v_and_or_b32 v17, v18, s61, v17
	flat_store_dwordx2 v[28:29], v[16:17] offset:1536
	v_mov_b32_e32 v16, v96
	v_fmamk_f32 v16, v16, 0x3a800000, v178
	v_cmp_gt_f32_e32 vcc, s28, v16
	v_mul_f32_e32 v17, 0x4f800000, v16
	s_nop 0
	v_cndmask_b32_e32 v16, v16, v17, vcc
	v_sqrt_f32_e32 v17, v16
	s_nop 0
	v_add_u32_e32 v18, -1, v17
	v_fma_f32 v19, -v18, v17, v16
	v_cmp_ge_f32_e64 s[0:1], 0, v19
	v_add_u32_e32 v19, 1, v17
	s_nop 0
	v_cndmask_b32_e64 v18, v17, v18, s[0:1]
	v_fma_f32 v17, -v19, v17, v16
	v_cmp_lt_f32_e64 s[0:1], 0, v17
	s_nop 1
	v_cndmask_b32_e64 v17, v18, v19, s[0:1]
	v_mul_f32_e32 v18, 0x37800000, v17
	v_cndmask_b32_e32 v17, v17, v18, vcc
	v_cmp_class_f32_e32 vcc, v16, v179
	s_nop 1
	v_cndmask_b32_e32 v16, v17, v16, vcc
	v_div_scale_f32 v17, s[0:1], v16, v16, 1.0
	v_rcp_f32_e32 v18, v17
	s_mov_b64 s[0:1], 0x3c0000
	v_lshl_add_u64 v[40:41], v[40:41], 0, s[0:1]
	v_fma_f32 v19, -v17, v18, 1.0
	v_fmac_f32_e32 v18, v19, v18
	v_div_scale_f32 v19, vcc, 1.0, v16, 1.0
	v_mul_f32_e32 v20, v19, v18
	v_fma_f32 v21, -v17, v20, v19
	v_fmac_f32_e32 v20, v21, v18
	v_fma_f32 v17, -v17, v20, v19
	v_div_fmas_f32 v17, v17, v18, v20
	v_div_fixup_f32 v16, v17, v16, 1.0
	v_mul_f32_e32 v12, v12, v16
	v_mul_f32_e32 v13, v13, v16
	v_mul_f32_e32 v8, v8, v16
	v_mul_f32_e32 v9, v9, v16
	v_mul_f32_e32 v4, v4, v16
	v_mul_f32_e32 v5, v5, v16
	v_mul_f32_e32 v0, v0, v16
	v_mul_f32_e32 v1, v1, v16
	v_mul_f32_e32 v12, v64, v12
	v_mul_f32_e32 v13, v65, v13
	v_bfe_u32 v17, v12, 16, 1
	v_add3_u32 v12, v12, v17, s60
	v_bfe_u32 v17, v13, 16, 1
	v_lshrrev_b32_e32 v12, 16, v12
	v_add3_u32 v13, v13, v17, s60
	v_and_or_b32 v12, v13, s61, v12
	v_mul_f32_e32 v13, v14, v16
	v_mul_f32_e32 v13, v66, v13
	v_mul_f32_e32 v14, v15, v16
	v_mul_f32_e32 v14, v67, v14
	v_bfe_u32 v15, v13, 16, 1
	v_add3_u32 v13, v13, v15, s60
	v_bfe_u32 v15, v14, 16, 1
	v_lshrrev_b32_e32 v13, 16, v13
	v_add3_u32 v14, v14, v15, s60
	v_and_or_b32 v13, v14, s61, v13
	flat_store_dwordx2 v[28:29], v[12:13] offset:2048
	v_mul_f32_e32 v8, v68, v8
	v_mul_f32_e32 v9, v69, v9
	v_bfe_u32 v12, v8, 16, 1
	v_add3_u32 v8, v8, v12, s60
	v_bfe_u32 v12, v9, 16, 1
	v_lshrrev_b32_e32 v8, 16, v8
	v_add3_u32 v9, v9, v12, s60
	v_and_or_b32 v8, v9, s61, v8
	v_mul_f32_e32 v9, v10, v16
	v_mul_f32_e32 v9, v70, v9
	v_mul_f32_e32 v10, v11, v16
	v_mul_f32_e32 v10, v71, v10
	v_bfe_u32 v11, v9, 16, 1
	v_add3_u32 v9, v9, v11, s60
	v_bfe_u32 v11, v10, 16, 1
	v_lshrrev_b32_e32 v9, 16, v9
	v_add3_u32 v10, v10, v11, s60
	v_and_or_b32 v9, v10, s61, v9
	flat_store_dwordx2 v[28:29], v[8:9] offset:2560
	v_mul_f32_e32 v4, v72, v4
	v_mul_f32_e32 v5, v73, v5
	v_bfe_u32 v8, v4, 16, 1
	v_add3_u32 v4, v4, v8, s60
	v_bfe_u32 v8, v5, 16, 1
	v_lshrrev_b32_e32 v4, 16, v4
	v_add3_u32 v5, v5, v8, s60
	v_and_or_b32 v4, v5, s61, v4
	v_mul_f32_e32 v5, v6, v16
	v_mul_f32_e32 v5, v74, v5
	v_mul_f32_e32 v6, v7, v16
	v_mul_f32_e32 v6, v75, v6
	v_bfe_u32 v7, v5, 16, 1
	v_add3_u32 v5, v5, v7, s60
	v_bfe_u32 v7, v6, 16, 1
	v_lshrrev_b32_e32 v5, 16, v5
	v_add3_u32 v6, v6, v7, s60
	v_and_or_b32 v5, v6, s61, v5
	flat_store_dwordx2 v[28:29], v[4:5] offset:3072
	v_mul_f32_e32 v0, v0, v76
	v_mul_f32_e32 v1, v1, v77
	v_bfe_u32 v4, v0, 16, 1
	v_add3_u32 v0, v0, v4, s60
	v_bfe_u32 v4, v1, 16, 1
	v_lshrrev_b32_e32 v0, 16, v0
	v_add3_u32 v1, v1, v4, s60
	v_and_or_b32 v0, v1, s61, v0
	v_mul_f32_e32 v1, v2, v16
	v_mul_f32_e32 v1, v1, v78
	v_mul_f32_e32 v2, v3, v16
	v_mul_f32_e32 v2, v2, v79
	v_bfe_u32 v3, v1, 16, 1
	v_add3_u32 v1, v1, v3, s60
	v_bfe_u32 v3, v2, 16, 1
	v_lshrrev_b32_e32 v1, 16, v1
	v_add3_u32 v2, v2, v3, s60
	v_and_or_b32 v1, v2, s61, v1
	flat_store_dwordx2 v[28:29], v[0:1] offset:3584
	s_cbranch_scc0 .LBB0_183
